# scan stage 0 LoRA MFMA loop unrolled with 4 operand sets, stage 3 operand reads all up front; norm_rows: next-row prefetch into spare VGPR bank (prompt rows)
# speedup vs baseline: 1.0162x; 1.0009x over previous
.LBB0_514:
	v_mov_b32_e32 v3, v71
	s_waitcnt vmcnt(0)
	ds_write_b128 v124, v[54:57]
	ds_write_b128 v125, v[58:61]
	ds_write_b128 v126, v[62:65]
	s_waitcnt lgkmcnt(0)
	s_barrier
	v_readlane_b32 s4, v253, 58
	v_and_b32_e32 v4, 31, v3
	v_ashrrev_i32_e32 v3, 5, v3
	v_mul_u32_u24_e32 v22, 0x310, v4
	v_or_b32_e32 v5, s72, v4
	v_lshlrev_b32_e32 v23, 4, v3
	v_mul_u32_u24_e32 v5, s4, v5
	v_add3_u32 v38, v22, v23, s87
	v_mov_b32_e32 v22, 0
	v_add3_u32 v5, v5, v23, s81
	s_mov_b32 s4, s80
	v_mov_b32_e32 v23, v22
	v_mov_b32_e32 v24, v22
	v_mov_b32_e32 v25, v22
	v_mov_b32_e32 v26, v22
	v_mov_b32_e32 v27, v22
	v_mov_b32_e32 v28, v22
	v_mov_b32_e32 v29, v22
	v_mov_b32_e32 v30, v22
	v_mov_b32_e32 v31, v22
	v_mov_b32_e32 v32, v22
	v_mov_b32_e32 v33, v22
	v_mov_b32_e32 v34, v22
	v_mov_b32_e32 v35, v22
	v_mov_b32_e32 v36, v22
	v_mov_b32_e32 v37, v22
	ds_read_b128 v[40:43], v38
	ds_read_b128 v[44:47], v5
	ds_read_b128 v[54:57], v38 offset:32
	ds_read_b128 v[58:61], v5 offset:32
	s_cmp_eq_u32 s4, 2
	s_cbranch_scc1 .Lrs0_fin2_515
	ds_read_b128 v[176:179], v38 offset:64
	ds_read_b128 v[180:183], v5 offset:64
	ds_read_b128 v[184:187], v38 offset:96
	ds_read_b128 v[188:191], v5 offset:96
	s_waitcnt lgkmcnt(6)
	v_mfma_f32_32x32x16_bf16 v[22:37], v[40:43], v[44:47], v[22:37]
	s_waitcnt lgkmcnt(4)
	v_mfma_f32_32x32x16_bf16 v[22:37], v[54:57], v[58:61], v[22:37]
	s_cmp_eq_u32 s4, 4
	s_cbranch_scc1 .Lrs0_fin4_515
	ds_read_b128 v[40:43], v38 offset:128
	ds_read_b128 v[44:47], v5 offset:128
	ds_read_b128 v[54:57], v38 offset:160
	ds_read_b128 v[58:61], v5 offset:160
	s_waitcnt lgkmcnt(6)
	v_mfma_f32_32x32x16_bf16 v[22:37], v[176:179], v[180:183], v[22:37]
	s_waitcnt lgkmcnt(4)
	v_mfma_f32_32x32x16_bf16 v[22:37], v[184:187], v[188:191], v[22:37]
	ds_read_b128 v[176:179], v38 offset:192
	ds_read_b128 v[180:183], v5 offset:192
	ds_read_b128 v[184:187], v38 offset:224
	ds_read_b128 v[188:191], v5 offset:224
	s_waitcnt lgkmcnt(6)
	v_mfma_f32_32x32x16_bf16 v[22:37], v[40:43], v[44:47], v[22:37]
	s_waitcnt lgkmcnt(4)
	v_mfma_f32_32x32x16_bf16 v[22:37], v[54:57], v[58:61], v[22:37]
	ds_read_b128 v[40:43], v38 offset:256
	ds_read_b128 v[44:47], v5 offset:256
	ds_read_b128 v[54:57], v38 offset:288
	ds_read_b128 v[58:61], v5 offset:288
	s_waitcnt lgkmcnt(6)
	v_mfma_f32_32x32x16_bf16 v[22:37], v[176:179], v[180:183], v[22:37]
	s_waitcnt lgkmcnt(4)
	v_mfma_f32_32x32x16_bf16 v[22:37], v[184:187], v[188:191], v[22:37]
	s_waitcnt lgkmcnt(2)
	v_mfma_f32_32x32x16_bf16 v[22:37], v[40:43], v[44:47], v[22:37]
	s_waitcnt lgkmcnt(0)
	v_mfma_f32_32x32x16_bf16 v[22:37], v[54:57], v[58:61], v[22:37]
	s_branch .Lrs0_done_515
.Lrs0_fin2_515:
	s_waitcnt lgkmcnt(2)
	v_mfma_f32_32x32x16_bf16 v[22:37], v[40:43], v[44:47], v[22:37]
	s_waitcnt lgkmcnt(0)
	v_mfma_f32_32x32x16_bf16 v[22:37], v[54:57], v[58:61], v[22:37]
	s_branch .Lrs0_done_515
.Lrs0_fin4_515:
	s_waitcnt lgkmcnt(2)
	v_mfma_f32_32x32x16_bf16 v[22:37], v[176:179], v[180:183], v[22:37]
	s_waitcnt lgkmcnt(0)
	v_mfma_f32_32x32x16_bf16 v[22:37], v[184:187], v[188:191], v[22:37]
.Lrs0_done_515:
	s_nop 3
	s_movk_i32 s5, 0x240
	v_lshlrev_b32_e32 v4, 1, v4
	v_mul_lo_u32 v3, v3, s5
	v_readlane_b32 s5, v253, 60
	s_lshl_b32 s4, s85, 5
	s_nop 0
	v_add3_u32 v3, s5, v4, v3
	v_cvt_pk_bf16_f32 v4, v22, v2
	ds_write_b16 v3, v4
	v_cvt_pk_bf16_f32 v4, v23, v2
	ds_write_b16 v3, v4 offset:144
	v_cvt_pk_bf16_f32 v4, v24, v2
	ds_write_b16 v3, v4 offset:288
	v_cvt_pk_bf16_f32 v4, v25, v2
	ds_write_b16 v3, v4 offset:432
	v_cvt_pk_bf16_f32 v4, v26, v2
	ds_write_b16 v3, v4 offset:1152
	v_cvt_pk_bf16_f32 v4, v27, v2
	ds_write_b16 v3, v4 offset:1296
	v_cvt_pk_bf16_f32 v4, v28, v2
	ds_write_b16 v3, v4 offset:1440
	v_cvt_pk_bf16_f32 v4, v29, v2
	ds_write_b16 v3, v4 offset:1584
	v_cvt_pk_bf16_f32 v4, v30, v2
	ds_write_b16 v3, v4 offset:2304
	v_cvt_pk_bf16_f32 v4, v31, v2
	ds_write_b16 v3, v4 offset:2448
	v_cvt_pk_bf16_f32 v4, v32, v2
	ds_write_b16 v3, v4 offset:2592
	v_cvt_pk_bf16_f32 v4, v33, v2
	ds_write_b16 v3, v4 offset:2736
	v_cvt_pk_bf16_f32 v4, v34, v2
	ds_write_b16 v3, v4 offset:3456
	v_cvt_pk_bf16_f32 v4, v35, v2
	s_add_i32 s5, s4, s73
	ds_write_b16 v3, v4 offset:3600
	v_cvt_pk_bf16_f32 v4, v36, v2
	s_cmp_lt_i32 s5, s82
	ds_write_b16 v3, v4 offset:3744
	v_cvt_pk_bf16_f32 v4, v37, v2
	ds_write_b16 v3, v4 offset:3888
	s_waitcnt lgkmcnt(0)
	s_barrier
	s_cbranch_scc0 .LBB0_518
	v_add_u32_e32 v4, s33, v109
	v_add_u32_e32 v23, s33, v110
	ds_read_u16 v4, v4
	ds_read_u16 v23, v23
	v_lshlrev_b32_e32 v3, 16, v131
	v_mul_f32_e32 v26, v145, v3
	v_lshlrev_b32_e32 v30, 16, v130
	s_waitcnt lgkmcnt(1)
	v_lshlrev_b32_e32 v4, 16, v4
	s_waitcnt lgkmcnt(0)
	v_lshlrev_b32_e32 v23, 16, v23
	v_add_f32_e32 v23, v144, v23
	v_mul_f32_e32 v23, 0xbfb8aa3b, v23
	v_exp_f32_e32 v23, v23
	v_add_f32_e32 v4, v143, v4
	v_mul_f32_e32 v4, 0xbfb8aa3b, v4
	v_exp_f32_e32 v4, v4
	v_add_f32_e32 v23, 1.0, v23
	v_rcp_f32_e32 v23, v23
	s_add_i32 s28, s5, s84
	s_ashr_i32 s29, s28, 31
	v_add_f32_e32 v4, 1.0, v4
	v_add_f32_e32 v24, -1.0, v23
	v_fma_f32 v24, v146, v24, 1.0
	v_mul_f32_e32 v31, v24, v3
	v_mul_f32_e32 v3, v26, v26
	v_mul_f32_e32 v24, v31, v30
	v_mul_f32_e32 v25, v147, v24
	v_mov_b32_dpp v3, v3 quad_perm:[1,0,3,2] row_mask:0xf bank_mask:0xf bound_ctrl:1
	v_fmac_f32_e32 v3, v26, v26
	v_mov_b32_dpp v25, v25 quad_perm:[1,0,3,2] row_mask:0xf bank_mask:0xf bound_ctrl:1
	v_fmac_f32_e32 v25, v147, v24
	v_add_f32_dpp v3, v3, v3 quad_perm:[2,3,0,1] row_mask:0xf bank_mask:0xf bound_ctrl:1
	s_lshl_b64 s[28:29], s[28:29], 12
	v_add_f32_dpp v24, v25, v25 quad_perm:[2,3,0,1] row_mask:0xf bank_mask:0xf bound_ctrl:1
	v_add_f32_dpp v3, v3, v3 row_ror:4 row_mask:0xf bank_mask:0xf bound_ctrl:1
	v_rcp_f32_e32 v22, v4
	v_add_f32_dpp v24, v24, v24 row_ror:4 row_mask:0xf bank_mask:0xf bound_ctrl:1
	v_add_f32_dpp v3, v3, v3 row_ror:8 row_mask:0xf bank_mask:0xf bound_ctrl:1
	v_lshl_add_u64 v[4:5], v[92:93], 0, s[28:29]
	v_readlane_b32 s5, v3, 16
	v_readlane_b32 s30, v3, 48
	v_add_f32_dpp v27, v24, v24 row_ror:8 row_mask:0xf bank_mask:0xf bound_ctrl:1
	v_readlane_b32 s28, v3, 0
	v_readlane_b32 s29, v3, 32
	v_mov_b32_e32 v24, s5
	v_mov_b32_e32 v25, s30
	v_pk_add_f32 v[24:25], s[28:29], v[24:25]
	v_readlane_b32 s5, v27, 16
	v_readlane_b32 s30, v27, 48
	v_add_f32_e32 v28, v24, v25
	v_readlane_b32 s28, v27, 0
	v_readlane_b32 s29, v27, 32
	v_mov_b32_e32 v24, s5
	v_mov_b32_e32 v25, s30
	v_pk_add_f32 v[24:25], s[28:29], v[24:25]
	s_nop 0
	v_add_f32_e32 v3, v24, v25
	v_sqrt_f32_e32 v24, v28
	v_lshlrev_b32_e32 v25, 16, v138
	global_store_dword v[4:5], v25, off
	v_xor_b32_e32 v24, 0x80000000, v24
	v_min_f32_e32 v24, 0xab8cbccc, v24
	v_rcp_f32_e32 v24, v24
	s_nop 0
	v_mul_f32_e32 v32, v26, v24
	v_add_u32_e32 v24, s33, v111
	ds_read_u16 v24, v24
	v_xor_b32_e32 v83, 0x80000000, v32
	v_pk_mul_f32 v[22:23], v[22:23], v[82:83]
	s_waitcnt lgkmcnt(0)
	v_lshlrev_b32_e32 v24, 16, v24
	s_branch .LBB0_519

.LBB0_540:
	v_mov_b32_e32 v4, v71
	v_readlane_b32 s8, v253, 50
	s_waitcnt lgkmcnt(0)
	s_barrier
	v_readlane_b32 s9, v253, 51
	v_and_b32_e32 v3, 31, v4
	v_ashrrev_i32_e32 v39, 5, v4
	v_lshlrev_b32_e32 v4, 4, v39
	v_mul_u32_u24_e32 v5, 0x90, v3
	s_mov_b64 s[34:35], -1
	s_and_b64 vcc, exec, s[8:9]
	s_cbranch_vccz .LBB0_542
	v_readlane_b32 s5, v253, 63
	v_or_b32_e32 v26, s72, v3
	v_mul_u32_u24_e32 v26, 0x90, v26
	v_add3_u32 v38, s5, v5, v4
	ds_read_b128 v[22:25], v38
	v_add3_u32 v48, 0, v26, v4
	ds_read_b128 v[26:29], v48 offset:41472
	ds_read_b128 v[40:43], v38 offset:32
	ds_read_b128 v[44:47], v48 offset:41504
	s_mov_b64 s[34:35], 0
	ds_read_b128 v[176:179], v38 offset:64
	ds_read_b128 v[180:183], v48 offset:41536
	ds_read_b128 v[184:187], v38 offset:96
	ds_read_b128 v[188:191], v48 offset:41568
	s_waitcnt lgkmcnt(6)
	v_mfma_f32_32x32x16_bf16 v[22:37], v[22:25], v[26:29], 0
	s_waitcnt lgkmcnt(4)
	v_mfma_f32_32x32x16_bf16 v[22:37], v[40:43], v[44:47], v[22:37]
	s_waitcnt lgkmcnt(2)
	v_mfma_f32_32x32x16_bf16 v[22:37], v[176:179], v[180:183], v[22:37]
	s_waitcnt lgkmcnt(0)
	v_mfma_f32_32x32x16_bf16 v[22:37], v[184:187], v[188:191], v[22:37]
.LBB0_542:
	s_andn2_b64 vcc, exec, s[34:35]
	s_cbranch_vccnz .LBB0_580
	v_readlane_b32 s5, v250, 0
	s_mov_b64 s[34:35], -1
	s_and_b64 vcc, exec, s[6:7]
	v_add3_u32 v38, s5, v5, v4
	s_nop 5
	ds_read_b128 v[22:25], v38
	v_readlane_b32 s5, v250, 2
	s_nop 1
	v_add3_u32 v4, s5, v5, v4
	ds_read_b128 v[26:29], v4
	ds_read_b128 v[40:43], v38 offset:32
	ds_read_b128 v[44:47], v4 offset:32
	ds_read_b128 v[176:179], v38 offset:64
	ds_read_b128 v[180:183], v4 offset:64
	ds_read_b128 v[184:187], v38 offset:96
	ds_read_b128 v[188:191], v4 offset:96
	s_waitcnt lgkmcnt(6)
	v_mfma_f32_32x32x16_bf16 v[22:37], v[22:25], v[26:29], 0
	v_readlane_b32 s5, v250, 8
	v_lshlrev_b32_e32 v5, 2, v39
	s_waitcnt lgkmcnt(4)
	v_mfma_f32_32x32x16_bf16 v[22:37], v[40:43], v[44:47], v[22:37]
	s_waitcnt lgkmcnt(2)
	v_mfma_f32_32x32x16_bf16 v[22:37], v[176:179], v[180:183], v[22:37]
	v_lshl_add_u32 v4, v3, 1, s5
	s_waitcnt lgkmcnt(0)
	v_mfma_f32_32x32x16_bf16 v[22:37], v[184:187], v[188:191], v[22:37]
	s_cbranch_vccz .LBB0_545
	v_cmp_lt_i32_e32 vcc, v3, v5
	s_movk_i32 s5, 0x140
	s_nop 0
	v_cndmask_b32_e64 v38, 0, 1, vcc
	v_cmp_le_i32_e32 vcc, v3, v5
	s_nop 1
	v_cndmask_b32_e64 v40, 0, 1, vcc
	v_cndmask_b32_e64 v38, v40, v38, s[96:97]
	v_and_b32_e32 v38, 1, v38
	v_cmp_eq_u32_e32 vcc, 1, v38
	v_mad_u64_u32 v[40:41], s[34:35], v39, s5, v[4:5]
	s_nop 0
	v_cndmask_b32_e32 v38, 0, v22, vcc
	v_cvt_pk_bf16_f32 v38, v38, v2
	ds_write_b16 v40, v38
	s_mov_b64 s[34:35], 0

.LBB0_787:
	s_or_b64 exec, exec, s[0:1]
	s_waitcnt lgkmcnt(0)
	v_mov_b32_e32 v2, v0
	s_barrier
	v_readlane_b32 s0, v252, 57
	v_lshrrev_b32_e32 v19, 6, v2
	v_mov_b32_e32 v18, v0
	v_add_u32_e32 v34, s0, v19
	s_mov_b32 s0, 0x8400
	v_cmp_gt_i32_e32 vcc, s0, v34
	s_and_saveexec_b64 s[2:3], vcc
	s_cbranch_execz .LBB0_798
	v_lshlrev_b32_e32 v2, 4, v18
	v_readlane_b32 s4, v252, 20
	v_and_b32_e32 v36, 0x3f0, v2
	v_readlane_b32 s6, v252, 22
	v_readlane_b32 s7, v252, 23
	s_nop 4
	global_load_dwordx4 v[2:5], v36, s[6:7]
	global_load_dwordx4 v[6:9], v36, s[6:7] offset:1024
	global_load_dwordx4 v[10:13], v36, s[6:7] offset:2048
	global_load_dwordx4 v[14:17], v36, s[6:7] offset:3072
	v_mbcnt_hi_u32_b32 v20, -1, v1
	v_and_b32_e32 v21, 64, v20
	v_add_u32_e32 v21, 64, v21
	v_xor_b32_e32 v22, 1, v20
	v_cmp_lt_i32_e32 vcc, v22, v21
	v_readlane_b32 s5, v252, 21
	v_readlane_b32 s8, v252, 24
	v_cndmask_b32_e32 v22, v20, v22, vcc
	v_lshlrev_b32_e32 v46, 2, v22
	v_xor_b32_e32 v22, 2, v20
	v_cmp_lt_i32_e32 vcc, v22, v21
	v_readlane_b32 s9, v252, 25
	v_readlane_b32 s10, v252, 26
	v_cndmask_b32_e32 v22, v20, v22, vcc
	v_lshlrev_b32_e32 v47, 2, v22
	v_xor_b32_e32 v22, 4, v20
	v_cmp_lt_i32_e32 vcc, v22, v21
	v_readlane_b32 s11, v252, 27
	v_readlane_b32 s12, v252, 28
	v_cndmask_b32_e32 v22, v20, v22, vcc
	v_lshlrev_b32_e32 v48, 2, v22
	v_xor_b32_e32 v22, 8, v20
	v_cmp_lt_i32_e32 vcc, v22, v21
	v_readlane_b32 s13, v252, 29
	v_readlane_b32 s14, v252, 30
	v_cndmask_b32_e32 v22, v20, v22, vcc
	v_lshlrev_b32_e32 v49, 2, v22
	v_xor_b32_e32 v22, 16, v20
	v_cmp_lt_i32_e32 vcc, v22, v21
	v_readlane_b32 s15, v252, 31
	v_readlane_b32 s16, v252, 32
	v_cndmask_b32_e32 v22, v20, v22, vcc
	v_lshlrev_b32_e32 v50, 2, v22
	v_xor_b32_e32 v22, 32, v20
	v_cmp_lt_i32_e32 vcc, v22, v21
	v_readlane_b32 s17, v252, 33
	v_readlane_b32 s18, v252, 34
	v_readlane_b32 s19, v252, 35
	v_cndmask_b32_e32 v20, v20, v22, vcc
	v_ashrrev_i32_e32 v35, 31, v34
	v_readlane_b32 s4, v252, 36
	v_lshlrev_b32_e32 v51, 2, v20
	v_readlane_b32 s0, v253, 28
	v_lshlrev_b64 v[20:21], 11, v[34:35]
	v_and_b32_e32 v22, 63, v18
	v_mov_b32_e32 v37, 0
	v_readlane_b32 s5, v252, 37
	v_readlane_b32 s12, v252, 44
	v_readlane_b32 s13, v252, 45
	v_lshlrev_b32_e32 v19, 8, v19
	v_readlane_b32 s1, v253, 29
	v_lshl_or_b32 v20, v22, 3, v20
	v_lshl_add_u64 v[38:39], s[12:13], 0, v[36:37]
	v_lshl_add_u32 v52, s34, 11, v19
	s_lshl_b32 s12, s0, 11
	v_lshl_add_u64 v[18:19], s[4:5], 0, v[20:21]
	s_mov_b64 s[0:1], 0x400
	v_lshl_add_u64 v[40:41], v[18:19], 0, s[0:1]
	v_readlane_b32 s0, v253, 30
	v_readlane_b32 s6, v252, 38
	v_readlane_b32 s7, v252, 39
	v_readlane_b32 s1, v253, 31
	v_lshlrev_b64 v[18:19], 12, v[34:35]
	v_readlane_b32 s8, v252, 40
	v_readlane_b32 s9, v252, 41
	s_mov_b32 s6, s0
	s_ashr_i32 s7, s0, 31
	v_lshl_or_b32 v18, v22, 4, v18
	v_writelane_b32 v253, s0, 30
	s_lshl_b64 s[4:5], s[6:7], 11
	v_lshl_add_u64 v[42:43], s[88:89], 0, v[18:19]
	v_writelane_b32 v253, s1, 31
	s_lshl_b64 s[6:7], s[6:7], 12
	s_mov_b64 s[8:9], 0
	v_mov_b32_e32 v35, 0x358637bd
	v_mov_b32_e32 v53, 0x260
	v_readlane_b32 s10, v252, 42
	v_readlane_b32 s11, v252, 43
	v_readlane_b32 s14, v252, 46
	v_readlane_b32 s15, v252, 47
	v_readlane_b32 s16, v252, 48
	v_readlane_b32 s17, v252, 49
	v_readlane_b32 s18, v252, 50
	v_readlane_b32 s19, v252, 51
	global_load_dwordx4 v[192:195], v[42:43], off
	global_load_dwordx4 v[196:199], v[42:43], off offset:1024
	global_load_dwordx4 v[200:203], v[42:43], off offset:2048
	global_load_dwordx4 v[204:207], v[42:43], off offset:3072
	s_waitcnt vmcnt(0)
	s_branch .LBB0_790

.Lnp_bp_790:
	ds_bpermute_b32 v44, v46, v36
	s_mov_b32 s0, 0xf800000
	v_add_u32_e32 v52, s12, v52
	v_lshl_add_u64 v[42:43], v[42:43], 0, s[6:7]
	global_load_dwordx4 v[192:195], v[42:43], off
	global_load_dwordx4 v[196:199], v[42:43], off offset:1024
	global_load_dwordx4 v[200:203], v[42:43], off offset:2048
	global_load_dwordx4 v[204:207], v[42:43], off offset:3072
	s_waitcnt lgkmcnt(0)
	v_add_f32_e32 v36, v36, v44
	ds_bpermute_b32 v44, v47, v36
	s_waitcnt lgkmcnt(0)
	v_add_f32_e32 v36, v36, v44
	ds_bpermute_b32 v44, v48, v36
	s_waitcnt lgkmcnt(0)
	v_add_f32_e32 v36, v36, v44
	ds_bpermute_b32 v44, v49, v36
	s_waitcnt lgkmcnt(0)
	v_add_f32_e32 v36, v36, v44
	ds_bpermute_b32 v44, v50, v36
	s_waitcnt lgkmcnt(0)
	v_add_f32_e32 v36, v36, v44
	ds_bpermute_b32 v44, v51, v36
	s_waitcnt lgkmcnt(0)
	v_add_f32_e32 v36, v36, v44
	v_fmamk_f32 v36, v36, 0x3a800000, v35
	v_mul_f32_e32 v44, 0x4f800000, v36
	v_cmp_gt_f32_e32 vcc, s0, v36
	s_nop 1
	v_cndmask_b32_e32 v36, v36, v44, vcc
	v_sqrt_f32_e32 v44, v36
	s_nop 0
	v_add_u32_e32 v45, -1, v44
	v_add_u32_e32 v54, 1, v44
	v_fma_f32 v55, -v45, v44, v36
	v_fma_f32 v56, -v54, v44, v36
	v_cmp_ge_f32_e64 s[0:1], 0, v55
	s_nop 1
	v_cndmask_b32_e64 v44, v44, v45, s[0:1]
	v_cmp_lt_f32_e64 s[0:1], 0, v56
	s_nop 1
	v_cndmask_b32_e64 v44, v44, v54, s[0:1]
	v_mul_f32_e32 v45, 0x37800000, v44
	v_cndmask_b32_e32 v44, v44, v45, vcc
	v_cmp_class_f32_e32 vcc, v36, v53
	s_nop 1
	v_cndmask_b32_e32 v36, v44, v36, vcc
	v_div_scale_f32 v44, s[0:1], v36, v36, 1.0
	v_rcp_f32_e32 v45, v44
	v_div_scale_f32 v54, vcc, 1.0, v36, 1.0
	v_readlane_b32 s0, v253, 30
	v_fma_f32 v55, -v44, v45, 1.0
	v_fmac_f32_e32 v45, v55, v45
	v_mul_f32_e32 v55, v54, v45
	v_fma_f32 v56, -v44, v55, v54
	v_fmac_f32_e32 v55, v56, v45
	v_fma_f32 v44, -v44, v55, v54
	v_div_fmas_f32 v44, v44, v45, v55
	v_div_fixup_f32 v36, v44, v36, 1.0
	v_mul_f32_e32 v18, v18, v36
	v_mul_f32_e32 v19, v19, v36
	v_mul_f32_e32 v20, v20, v36
	v_mul_f32_e32 v18, v2, v18
	v_mul_f32_e32 v19, v3, v19
	v_cvt_pk_bf16_f32 v18, v18, v19
	v_mul_f32_e32 v19, v4, v20
	v_mul_f32_e32 v20, v21, v36
	v_mul_f32_e32 v20, v5, v20
	v_cvt_pk_bf16_f32 v19, v19, v20
	global_store_dwordx2 v[40:41], v[18:19], off offset:-1024
	v_mul_f32_e32 v18, v22, v36
	v_mul_f32_e32 v19, v23, v36
	v_mul_f32_e32 v18, v6, v18
	v_mul_f32_e32 v19, v7, v19
	v_cvt_pk_bf16_f32 v18, v18, v19
	v_mul_f32_e32 v19, v24, v36
	v_mul_f32_e32 v19, v8, v19
	v_mul_f32_e32 v20, v25, v36
	v_mul_f32_e32 v20, v9, v20
	v_cvt_pk_bf16_f32 v19, v19, v20
	global_store_dwordx2 v[40:41], v[18:19], off offset:-512
	v_mul_f32_e32 v18, v26, v36
	v_mul_f32_e32 v19, v27, v36
	v_mul_f32_e32 v18, v10, v18
	v_mul_f32_e32 v19, v11, v19
	v_cvt_pk_bf16_f32 v18, v18, v19
	v_mul_f32_e32 v19, v28, v36
	v_mul_f32_e32 v19, v12, v19
	v_mul_f32_e32 v20, v29, v36
	v_mul_f32_e32 v20, v13, v20
	v_cvt_pk_bf16_f32 v19, v19, v20
	global_store_dwordx2 v[40:41], v[18:19], off
	v_mul_f32_e32 v18, v30, v36
	v_mul_f32_e32 v19, v31, v36
	v_mul_f32_e32 v18, v14, v18
	v_mul_f32_e32 v19, v15, v19
	v_cvt_pk_bf16_f32 v18, v18, v19
	v_mul_f32_e32 v19, v32, v36
	v_add_u32_e32 v34, s0, v34
	s_mov_b32 s0, 0x83ff
	v_mul_f32_e32 v19, v16, v19
	v_mul_f32_e32 v20, v33, v36
	v_cmp_lt_i32_e32 vcc, s0, v34
	v_mul_f32_e32 v20, v17, v20
	v_cvt_pk_bf16_f32 v19, v19, v20
	global_store_dwordx2 v[40:41], v[18:19], off offset:512
	v_lshl_add_u64 v[40:41], v[40:41], 0, s[4:5]
	s_or_b64 s[8:9], vcc, s[8:9]
	v_readlane_b32 s1, v253, 31
	s_andn2_b64 exec, exec, s[8:9]
	s_cbranch_execz .LBB0_798
.LBB0_790:
	v_cmp_gt_i32_e32 vcc, 0x8000, v34
	s_cbranch_vccz .Lnp_orig_790
	s_waitcnt vmcnt(4)
	v_mov_b64_e32 v[18:19], v[192:193]
	v_mov_b64_e32 v[20:21], v[194:195]
	v_mov_b64_e32 v[22:23], v[196:197]
	v_mov_b64_e32 v[24:25], v[198:199]
	v_mov_b64_e32 v[26:27], v[200:201]
	v_mov_b64_e32 v[28:29], v[202:203]
	v_mov_b64_e32 v[30:31], v[204:205]
	v_mov_b64_e32 v[32:33], v[206:207]
	v_mul_f32_e32 v36, v19, v19
	v_mul_f32_e32 v44, v21, v21
	v_fmac_f32_e32 v36, v18, v18
	v_fmac_f32_e32 v44, v20, v20
	v_add_f32_e32 v36, v36, v44
	v_mul_f32_e32 v44, v23, v23
	v_mul_f32_e32 v45, v25, v25
	v_fmac_f32_e32 v44, v22, v22
	v_fmac_f32_e32 v45, v24, v24
	v_add_f32_e32 v44, v44, v45
	v_add_f32_e32 v36, v36, v44
	v_mul_f32_e32 v44, v27, v27
	v_mul_f32_e32 v45, v29, v29
	v_fmac_f32_e32 v44, v26, v26
	v_fmac_f32_e32 v45, v28, v28
	v_add_f32_e32 v44, v44, v45
	v_add_f32_e32 v36, v36, v44
	v_mul_f32_e32 v44, v31, v31
	v_mul_f32_e32 v45, v33, v33
	v_fmac_f32_e32 v44, v30, v30
	v_fmac_f32_e32 v45, v32, v32
	v_add_f32_e32 v44, v44, v45
	v_add_f32_e32 v36, v36, v44
	s_branch .Lnp_bp_790

.LBB0_1033:
	s_or_b64 exec, exec, s[0:1]
	s_waitcnt lgkmcnt(0)
	v_mov_b32_e32 v2, v0
	s_barrier
	v_readlane_b32 s0, v252, 57
	v_lshrrev_b32_e32 v19, 6, v2
	v_mov_b32_e32 v18, v0
	v_add_u32_e32 v34, s0, v19
	s_mov_b32 s0, 0x8400
	v_cmp_gt_i32_e32 vcc, s0, v34
	s_and_saveexec_b64 s[2:3], vcc
	s_cbranch_execz .LBB0_1044
	v_lshlrev_b32_e32 v2, 4, v18
	v_readlane_b32 s4, v252, 20
	v_and_b32_e32 v36, 0x3f0, v2
	v_mov_b32_e32 v37, 0
	v_readlane_b32 s5, v252, 21
	s_mov_b64 s[0:1], 0x1000
	v_mbcnt_hi_u32_b32 v20, -1, v1
	v_lshl_add_u64 v[2:3], s[4:5], 0, v[36:37]
	v_add_co_u32_e32 v10, vcc, 0x1000, v2
	v_lshl_add_u64 v[14:15], v[2:3], 0, s[0:1]
	s_nop 0
	v_addc_co_u32_e32 v11, vcc, 0, v3, vcc
	global_load_dwordx4 v[2:5], v[14:15], off offset:1024
	global_load_dwordx4 v[6:9], v[14:15], off offset:2048
	s_nop 0
	global_load_dwordx4 v[10:13], v[10:11], off
	s_nop 0
	global_load_dwordx4 v[14:17], v[14:15], off offset:3072
	v_and_b32_e32 v21, 64, v20
	v_add_u32_e32 v21, 64, v21
	v_xor_b32_e32 v22, 1, v20
	v_cmp_lt_i32_e32 vcc, v22, v21
	v_readlane_b32 s8, v252, 24
	v_readlane_b32 s9, v252, 25
	v_cndmask_b32_e32 v22, v20, v22, vcc
	v_lshlrev_b32_e32 v46, 2, v22
	v_xor_b32_e32 v22, 2, v20
	v_cmp_lt_i32_e32 vcc, v22, v21
	v_readlane_b32 s10, v252, 26
	v_readlane_b32 s11, v252, 27
	v_cndmask_b32_e32 v22, v20, v22, vcc
	v_lshlrev_b32_e32 v47, 2, v22
	v_xor_b32_e32 v22, 4, v20
	v_cmp_lt_i32_e32 vcc, v22, v21
	v_readlane_b32 s12, v252, 28
	v_readlane_b32 s13, v252, 29
	v_cndmask_b32_e32 v22, v20, v22, vcc
	v_lshlrev_b32_e32 v48, 2, v22
	v_xor_b32_e32 v22, 8, v20
	v_cmp_lt_i32_e32 vcc, v22, v21
	v_readlane_b32 s14, v252, 30
	v_readlane_b32 s15, v252, 31
	v_cndmask_b32_e32 v22, v20, v22, vcc
	v_lshlrev_b32_e32 v49, 2, v22
	v_xor_b32_e32 v22, 16, v20
	v_cmp_lt_i32_e32 vcc, v22, v21
	v_readlane_b32 s16, v252, 32
	v_readlane_b32 s17, v252, 33
	v_cndmask_b32_e32 v22, v20, v22, vcc
	v_lshlrev_b32_e32 v50, 2, v22
	v_xor_b32_e32 v22, 32, v20
	v_cmp_lt_i32_e32 vcc, v22, v21
	v_readlane_b32 s18, v252, 34
	v_readlane_b32 s19, v252, 35
	v_cndmask_b32_e32 v20, v20, v22, vcc
	v_ashrrev_i32_e32 v35, 31, v34
	v_readlane_b32 s8, v252, 36
	v_lshlrev_b32_e32 v51, 2, v20
	v_readlane_b32 s0, v253, 28
	v_lshlrev_b64 v[20:21], 11, v[34:35]
	v_and_b32_e32 v22, 63, v18
	v_readlane_b32 s9, v252, 37
	v_lshlrev_b32_e32 v19, 8, v19
	v_readlane_b32 s1, v253, 29
	v_lshl_or_b32 v20, v22, 3, v20
	v_lshl_add_u32 v52, s34, 11, v19
	s_lshl_b32 s4, s0, 11
	v_lshl_add_u64 v[18:19], s[8:9], 0, v[20:21]
	s_mov_b64 s[0:1], 0x400
	v_lshl_add_u64 v[40:41], v[18:19], 0, s[0:1]
	v_readlane_b32 s0, v253, 30
	v_readlane_b32 s6, v252, 22
	v_readlane_b32 s7, v252, 23
	v_readlane_b32 s1, v253, 31
	v_lshlrev_b64 v[18:19], 12, v[34:35]
	v_readlane_b32 s10, v252, 38
	v_readlane_b32 s11, v252, 39
	v_readlane_b32 s12, v252, 40
	v_readlane_b32 s13, v252, 41
	v_readlane_b32 s16, v252, 44
	v_readlane_b32 s17, v252, 45
	s_mov_b32 s6, s0
	s_ashr_i32 s7, s0, 31
	v_lshl_or_b32 v18, v22, 4, v18
	v_writelane_b32 v253, s0, 30
	v_lshl_add_u64 v[38:39], s[16:17], 0, v[36:37]
	s_lshl_b64 s[8:9], s[6:7], 11
	v_lshl_add_u64 v[42:43], s[88:89], 0, v[18:19]
	v_writelane_b32 v253, s1, 31
	s_lshl_b64 s[10:11], s[6:7], 12
	s_mov_b64 s[12:13], 0
	v_mov_b32_e32 v35, 0x358637bd
	v_mov_b32_e32 v53, 0x260
	v_mov_b32_e32 v54, 0x80
	v_mov_b32_e32 v55, 0xc0
	v_readlane_b32 s14, v252, 42
	v_readlane_b32 s15, v252, 43
	v_readlane_b32 s18, v252, 46
	v_readlane_b32 s19, v252, 47
	v_readlane_b32 s20, v252, 48
	v_readlane_b32 s21, v252, 49
	v_readlane_b32 s22, v252, 50
	v_readlane_b32 s23, v252, 51
	global_load_dwordx4 v[192:195], v[42:43], off
	global_load_dwordx4 v[196:199], v[42:43], off offset:1024
	global_load_dwordx4 v[200:203], v[42:43], off offset:2048
	global_load_dwordx4 v[204:207], v[42:43], off offset:3072
	s_waitcnt vmcnt(0)
	s_branch .LBB0_1036

.Lnp_bp_1036:
	ds_bpermute_b32 v44, v46, v36
	s_mov_b32 s0, 0xf800000
	v_add_u32_e32 v52, s4, v52
	v_lshl_add_u64 v[42:43], v[42:43], 0, s[10:11]
	global_load_dwordx4 v[192:195], v[42:43], off
	global_load_dwordx4 v[196:199], v[42:43], off offset:1024
	global_load_dwordx4 v[200:203], v[42:43], off offset:2048
	global_load_dwordx4 v[204:207], v[42:43], off offset:3072
	s_waitcnt lgkmcnt(0)
	v_add_f32_e32 v36, v36, v44
	ds_bpermute_b32 v44, v47, v36
	s_waitcnt lgkmcnt(0)
	v_add_f32_e32 v36, v36, v44
	ds_bpermute_b32 v44, v48, v36
	s_waitcnt lgkmcnt(0)
	v_add_f32_e32 v36, v36, v44
	ds_bpermute_b32 v44, v49, v36
	s_waitcnt lgkmcnt(0)
	v_add_f32_e32 v36, v36, v44
	ds_bpermute_b32 v44, v50, v36
	s_waitcnt lgkmcnt(0)
	v_add_f32_e32 v36, v36, v44
	ds_bpermute_b32 v44, v51, v36
	s_waitcnt lgkmcnt(0)
	v_add_f32_e32 v36, v36, v44
	v_fmamk_f32 v36, v36, 0x3a800000, v35
	v_mul_f32_e32 v44, 0x4f800000, v36
	v_cmp_gt_f32_e32 vcc, s0, v36
	s_nop 1
	v_cndmask_b32_e32 v36, v36, v44, vcc
	v_sqrt_f32_e32 v44, v36
	s_nop 0
	v_add_u32_e32 v45, -1, v44
	v_add_u32_e32 v56, 1, v44
	v_fma_f32 v57, -v45, v44, v36
	v_fma_f32 v58, -v56, v44, v36
	v_cmp_ge_f32_e64 s[0:1], 0, v57
	s_nop 1
	v_cndmask_b32_e64 v44, v44, v45, s[0:1]
	v_cmp_lt_f32_e64 s[0:1], 0, v58
	s_nop 1
	v_cndmask_b32_e64 v44, v44, v56, s[0:1]
	v_mul_f32_e32 v45, 0x37800000, v44
	v_cndmask_b32_e32 v44, v44, v45, vcc
	v_cmp_class_f32_e32 vcc, v36, v53
	s_nop 1
	v_cndmask_b32_e32 v36, v44, v36, vcc
	v_div_scale_f32 v44, s[0:1], v36, v36, 1.0
	v_rcp_f32_e32 v45, v44
	v_div_scale_f32 v56, vcc, 1.0, v36, 1.0
	v_readlane_b32 s0, v253, 30
	v_fma_f32 v57, -v44, v45, 1.0
	v_fmac_f32_e32 v45, v57, v45
	v_mul_f32_e32 v57, v56, v45
	v_fma_f32 v58, -v44, v57, v56
	v_fmac_f32_e32 v57, v58, v45
	v_fma_f32 v44, -v44, v57, v56
	v_div_fmas_f32 v44, v44, v45, v57
	v_div_fixup_f32 v36, v44, v36, 1.0
	v_mul_f32_e32 v18, v18, v36
	v_mul_f32_e32 v19, v19, v36
	v_mul_f32_e32 v20, v20, v36
	v_mul_f32_e32 v18, v10, v18
	v_mul_f32_e32 v19, v11, v19
	v_cvt_pk_bf16_f32 v18, v18, v19
	v_mul_f32_e32 v19, v12, v20
	v_mul_f32_e32 v20, v21, v36
	v_mul_f32_e32 v20, v13, v20
	v_cvt_pk_bf16_f32 v19, v19, v20
	global_store_dwordx2 v[40:41], v[18:19], off offset:-1024
	v_mul_f32_e32 v18, v22, v36
	v_mul_f32_e32 v19, v23, v36
	v_mul_f32_e32 v18, v2, v18
	v_mul_f32_e32 v19, v3, v19
	v_cvt_pk_bf16_f32 v18, v18, v19
	v_mul_f32_e32 v19, v24, v36
	v_mul_f32_e32 v19, v4, v19
	v_mul_f32_e32 v20, v25, v36
	v_mul_f32_e32 v20, v5, v20
	v_cvt_pk_bf16_f32 v19, v19, v20
	global_store_dwordx2 v[40:41], v[18:19], off offset:-512
	v_mul_f32_e32 v18, v26, v36
	v_mul_f32_e32 v19, v27, v36
	v_mul_f32_e32 v18, v6, v18
	v_mul_f32_e32 v19, v7, v19
	v_cvt_pk_bf16_f32 v18, v18, v19
	v_mul_f32_e32 v19, v28, v36
	v_mul_f32_e32 v19, v8, v19
	v_mul_f32_e32 v20, v29, v36
	v_mul_f32_e32 v20, v9, v20
	v_cvt_pk_bf16_f32 v19, v19, v20
	global_store_dwordx2 v[40:41], v[18:19], off
	v_mul_f32_e32 v18, v30, v36
	v_mul_f32_e32 v19, v31, v36
	v_mul_f32_e32 v18, v14, v18
	v_mul_f32_e32 v19, v15, v19
	v_cvt_pk_bf16_f32 v18, v18, v19
	v_mul_f32_e32 v19, v32, v36
	v_add_u32_e32 v34, s0, v34
	s_mov_b32 s0, 0x83ff
	v_mul_f32_e32 v19, v16, v19
	v_mul_f32_e32 v20, v33, v36
	v_cmp_lt_i32_e32 vcc, s0, v34
	v_mul_f32_e32 v20, v17, v20
	v_cvt_pk_bf16_f32 v19, v19, v20
	global_store_dwordx2 v[40:41], v[18:19], off offset:512
	v_lshl_add_u64 v[40:41], v[40:41], 0, s[8:9]
	s_or_b64 s[12:13], vcc, s[12:13]
	v_readlane_b32 s1, v253, 31
	s_andn2_b64 exec, exec, s[12:13]
	s_cbranch_execz .LBB0_1044

.LBB0_1867:
	s_or_b64 exec, exec, s[0:1]
	s_waitcnt lgkmcnt(0)
	v_mov_b32_e32 v2, v0
	s_barrier
	v_readlane_b32 s0, v252, 57
	v_lshrrev_b32_e32 v19, 6, v2
	v_mov_b32_e32 v18, v0
	v_add_u32_e32 v34, s0, v19
	s_mov_b32 s0, 0x8400
	v_cmp_gt_i32_e32 vcc, s0, v34
	s_and_saveexec_b64 s[2:3], vcc
	s_cbranch_execz .LBB0_1878
	v_lshlrev_b32_e32 v2, 4, v18
	v_readlane_b32 s4, v252, 20
	v_and_b32_e32 v36, 0x3f0, v2
	v_mov_b32_e32 v37, 0
	v_readlane_b32 s6, v252, 22
	v_readlane_b32 s7, v252, 23
	s_mov_b64 s[0:1], 0x1000
	v_readlane_b32 s8, v252, 24
	v_lshl_add_u64 v[2:3], s[6:7], 0, v[36:37]
	v_add_co_u32_e32 v10, vcc, 0x1000, v2
	v_lshl_add_u64 v[14:15], v[2:3], 0, s[0:1]
	s_nop 0
	v_addc_co_u32_e32 v11, vcc, 0, v3, vcc
	global_load_dwordx4 v[2:5], v[14:15], off offset:1024
	global_load_dwordx4 v[6:9], v[14:15], off offset:2048
	s_nop 0
	global_load_dwordx4 v[10:13], v[10:11], off
	s_nop 0
	global_load_dwordx4 v[14:17], v[14:15], off offset:3072
	v_readlane_b32 s9, v252, 25
	v_readlane_b32 s10, v252, 26
	v_readlane_b32 s11, v252, 27
	v_readlane_b32 s12, v252, 28
	v_readlane_b32 s13, v252, 29
	v_readlane_b32 s14, v252, 30
	v_readlane_b32 s15, v252, 31
	v_readlane_b32 s16, v252, 32
	v_readlane_b32 s17, v252, 33
	v_readlane_b32 s18, v252, 34
	v_readlane_b32 s19, v252, 35
	v_ashrrev_i32_e32 v35, 31, v34
	v_readlane_b32 s8, v252, 36
	v_readlane_b32 s0, v253, 28
	v_lshlrev_b64 v[20:21], 11, v[34:35]
	v_and_b32_e32 v22, 63, v18
	v_readlane_b32 s9, v252, 37
	v_lshlrev_b32_e32 v19, 8, v19
	v_readlane_b32 s1, v253, 29
	v_lshl_or_b32 v20, v22, 3, v20
	v_lshl_add_u32 v46, s96, 11, v19
	s_lshl_b32 s4, s0, 11
	v_lshl_add_u64 v[18:19], s[8:9], 0, v[20:21]
	s_mov_b64 s[0:1], 0x400
	v_lshl_add_u64 v[40:41], v[18:19], 0, s[0:1]
	v_lshlrev_b64 v[18:19], 12, v[34:35]
	v_readlane_b32 s10, v252, 38
	v_readlane_b32 s11, v252, 39
	v_readlane_b32 s16, v252, 44
	v_readlane_b32 s17, v252, 45
	s_ashr_i32 s61, s60, 31
	v_lshl_or_b32 v18, v22, 4, v18
	v_lshl_add_u64 v[38:39], s[16:17], 0, v[36:37]
	s_lshl_b64 s[6:7], s[60:61], 11
	v_lshl_add_u64 v[42:43], s[88:89], 0, v[18:19]
	s_lshl_b64 s[8:9], s[60:61], 12
	s_mov_b64 s[10:11], 0
	v_mov_b32_e32 v35, 0x358637bd
	v_mov_b32_e32 v47, 0x260
	v_readlane_b32 s5, v252, 21
	v_readlane_b32 s12, v252, 40
	v_readlane_b32 s13, v252, 41
	v_readlane_b32 s14, v252, 42
	v_readlane_b32 s15, v252, 43
	v_readlane_b32 s18, v252, 46
	v_readlane_b32 s19, v252, 47
	v_readlane_b32 s20, v252, 48
	v_readlane_b32 s21, v252, 49
	v_readlane_b32 s22, v252, 50
	v_readlane_b32 s23, v252, 51
	global_load_dwordx4 v[192:195], v[42:43], off
	global_load_dwordx4 v[196:199], v[42:43], off offset:1024
	global_load_dwordx4 v[200:203], v[42:43], off offset:2048
	global_load_dwordx4 v[204:207], v[42:43], off offset:3072
	s_waitcnt vmcnt(0)
	s_branch .LBB0_1870

.Lnp_bp_1870:
	ds_bpermute_b32 v44, v1, v36
	s_mov_b32 s0, 0xf800000
	v_add_u32_e32 v34, s60, v34
	v_add_u32_e32 v46, s4, v46
	v_lshl_add_u64 v[42:43], v[42:43], 0, s[8:9]
	global_load_dwordx4 v[192:195], v[42:43], off
	global_load_dwordx4 v[196:199], v[42:43], off offset:1024
	global_load_dwordx4 v[200:203], v[42:43], off offset:2048
	global_load_dwordx4 v[204:207], v[42:43], off offset:3072
	s_waitcnt lgkmcnt(0)
	v_add_f32_e32 v36, v36, v44
	ds_bpermute_b32 v44, v234, v36
	s_waitcnt lgkmcnt(0)
	v_add_f32_e32 v36, v36, v44
	ds_bpermute_b32 v44, v235, v36
	s_waitcnt lgkmcnt(0)
	v_add_f32_e32 v36, v36, v44
	ds_bpermute_b32 v44, v236, v36
	s_waitcnt lgkmcnt(0)
	v_add_f32_e32 v36, v36, v44
	ds_bpermute_b32 v44, v237, v36
	s_waitcnt lgkmcnt(0)
	v_add_f32_e32 v36, v36, v44
	ds_bpermute_b32 v44, v238, v36
	s_waitcnt lgkmcnt(0)
	v_add_f32_e32 v36, v36, v44
	v_fmamk_f32 v36, v36, 0x3a800000, v35
	v_mul_f32_e32 v44, 0x4f800000, v36
	v_cmp_gt_f32_e32 vcc, s0, v36
	s_nop 1
	v_cndmask_b32_e32 v36, v36, v44, vcc
	v_sqrt_f32_e32 v44, v36
	s_nop 0
	v_add_u32_e32 v45, -1, v44
	v_add_u32_e32 v48, 1, v44
	v_fma_f32 v49, -v45, v44, v36
	v_fma_f32 v50, -v48, v44, v36
	v_cmp_ge_f32_e64 s[0:1], 0, v49
	s_nop 1
	v_cndmask_b32_e64 v44, v44, v45, s[0:1]
	v_cmp_lt_f32_e64 s[0:1], 0, v50
	s_nop 1
	v_cndmask_b32_e64 v44, v44, v48, s[0:1]
	v_mul_f32_e32 v45, 0x37800000, v44
	v_cndmask_b32_e32 v44, v44, v45, vcc
	v_cmp_class_f32_e32 vcc, v36, v47
	s_nop 1
	v_cndmask_b32_e32 v36, v44, v36, vcc
	v_div_scale_f32 v44, s[0:1], v36, v36, 1.0
	v_rcp_f32_e32 v45, v44
	v_div_scale_f32 v48, vcc, 1.0, v36, 1.0
	s_mov_b32 s0, 0x83ff
	v_fma_f32 v49, -v44, v45, 1.0
	v_fmac_f32_e32 v45, v49, v45
	v_mul_f32_e32 v49, v48, v45
	v_fma_f32 v50, -v44, v49, v48
	v_fmac_f32_e32 v49, v50, v45
	v_fma_f32 v44, -v44, v49, v48
	v_div_fmas_f32 v44, v44, v45, v49
	v_div_fixup_f32 v36, v44, v36, 1.0
	v_mul_f32_e32 v18, v18, v36
	v_mul_f32_e32 v19, v19, v36
	v_mul_f32_e32 v20, v20, v36
	v_mul_f32_e32 v18, v10, v18
	v_mul_f32_e32 v19, v11, v19
	v_cvt_pk_bf16_f32 v18, v18, v19
	v_mul_f32_e32 v19, v12, v20
	v_mul_f32_e32 v20, v21, v36
	v_mul_f32_e32 v20, v13, v20
	v_cvt_pk_bf16_f32 v19, v19, v20
	global_store_dwordx2 v[40:41], v[18:19], off offset:-1024
	v_mul_f32_e32 v18, v22, v36
	v_mul_f32_e32 v19, v23, v36
	v_mul_f32_e32 v18, v2, v18
	v_mul_f32_e32 v19, v3, v19
	v_cvt_pk_bf16_f32 v18, v18, v19
	v_mul_f32_e32 v19, v24, v36
	v_mul_f32_e32 v19, v4, v19
	v_mul_f32_e32 v20, v25, v36
	v_mul_f32_e32 v20, v5, v20
	v_cvt_pk_bf16_f32 v19, v19, v20
	global_store_dwordx2 v[40:41], v[18:19], off offset:-512
	v_mul_f32_e32 v18, v26, v36
	v_mul_f32_e32 v19, v27, v36
	v_mul_f32_e32 v18, v6, v18
	v_mul_f32_e32 v19, v7, v19
	v_cvt_pk_bf16_f32 v18, v18, v19
	v_mul_f32_e32 v19, v28, v36
	v_mul_f32_e32 v19, v8, v19
	v_mul_f32_e32 v20, v29, v36
	v_mul_f32_e32 v20, v9, v20
	v_cvt_pk_bf16_f32 v19, v19, v20
	global_store_dwordx2 v[40:41], v[18:19], off
	v_mul_f32_e32 v18, v30, v36
	v_mul_f32_e32 v19, v31, v36
	v_mul_f32_e32 v18, v14, v18
	v_mul_f32_e32 v19, v15, v19
	v_cvt_pk_bf16_f32 v18, v18, v19
	v_mul_f32_e32 v19, v32, v36
	v_mul_f32_e32 v19, v16, v19
	v_mul_f32_e32 v20, v33, v36
	v_cmp_lt_i32_e32 vcc, s0, v34
	v_mul_f32_e32 v20, v17, v20
	v_cvt_pk_bf16_f32 v19, v19, v20
	global_store_dwordx2 v[40:41], v[18:19], off offset:512
	v_lshl_add_u64 v[40:41], v[40:41], 0, s[6:7]
	s_or_b64 s[10:11], vcc, s[10:11]
	s_andn2_b64 exec, exec, s[10:11]
	s_cbranch_execz .LBB0_1878

.LBB0_2151:
	s_or_b64 exec, exec, s[0:1]
	s_waitcnt lgkmcnt(0)
	v_mov_b32_e32 v2, v0
	s_barrier
	v_readlane_b32 s0, v252, 57
	v_lshrrev_b32_e32 v19, 6, v2
	v_mov_b32_e32 v18, v0
	v_add_u32_e32 v34, s0, v19
	s_mov_b32 s0, 0x8400
	v_cmp_gt_i32_e32 vcc, s0, v34
	s_and_saveexec_b64 s[2:3], vcc
	s_cbranch_execz .LBB0_2162
	v_lshlrev_b32_e32 v2, 4, v18
	v_readlane_b32 s4, v252, 20
	v_and_b32_e32 v36, 0x3f0, v2
	v_mov_b32_e32 v37, 0
	v_readlane_b32 s5, v252, 21
	s_mov_b64 s[0:1], 0x2000
	v_readlane_b32 s8, v252, 24
	v_lshl_add_u64 v[2:3], s[4:5], 0, v[36:37]
	v_add_co_u32_e32 v10, vcc, 0x2000, v2
	v_lshl_add_u64 v[14:15], v[2:3], 0, s[0:1]
	s_nop 0
	v_addc_co_u32_e32 v11, vcc, 0, v3, vcc
	global_load_dwordx4 v[2:5], v[14:15], off offset:1024
	global_load_dwordx4 v[6:9], v[14:15], off offset:2048
	s_nop 0
	global_load_dwordx4 v[10:13], v[10:11], off
	s_nop 0
	global_load_dwordx4 v[14:17], v[14:15], off offset:3072
	v_readlane_b32 s9, v252, 25
	v_readlane_b32 s10, v252, 26
	v_readlane_b32 s11, v252, 27
	v_readlane_b32 s12, v252, 28
	v_readlane_b32 s13, v252, 29
	v_readlane_b32 s14, v252, 30
	v_readlane_b32 s15, v252, 31
	v_readlane_b32 s16, v252, 32
	v_readlane_b32 s17, v252, 33
	v_readlane_b32 s18, v252, 34
	v_readlane_b32 s19, v252, 35
	v_ashrrev_i32_e32 v35, 31, v34
	v_readlane_b32 s8, v252, 36
	v_readlane_b32 s0, v253, 28
	v_lshlrev_b64 v[20:21], 11, v[34:35]
	v_and_b32_e32 v22, 63, v18
	v_readlane_b32 s9, v252, 37
	v_lshlrev_b32_e32 v19, 8, v19
	v_readlane_b32 s1, v253, 29
	v_lshl_or_b32 v20, v22, 3, v20
	v_lshl_add_u32 v46, s96, 11, v19
	s_lshl_b32 s4, s0, 11
	v_lshl_add_u64 v[18:19], s[8:9], 0, v[20:21]
	s_mov_b64 s[0:1], 0x400
	v_lshl_add_u64 v[40:41], v[18:19], 0, s[0:1]
	v_lshlrev_b64 v[18:19], 12, v[34:35]
	v_readlane_b32 s10, v252, 38
	v_readlane_b32 s11, v252, 39
	v_readlane_b32 s12, v252, 40
	v_readlane_b32 s13, v252, 41
	v_readlane_b32 s16, v252, 44
	v_readlane_b32 s17, v252, 45
	s_ashr_i32 s61, s60, 31
	v_lshl_or_b32 v18, v22, 4, v18
	v_lshl_add_u64 v[38:39], s[16:17], 0, v[36:37]
	s_lshl_b64 s[8:9], s[60:61], 11
	v_lshl_add_u64 v[42:43], s[88:89], 0, v[18:19]
	s_lshl_b64 s[10:11], s[60:61], 12
	s_mov_b64 s[12:13], 0
	v_mov_b32_e32 v35, 0x358637bd
	v_mov_b32_e32 v47, 0x260
	v_mov_b32_e32 v48, 0x80
	v_mov_b32_e32 v49, 0xc0
	v_readlane_b32 s6, v252, 22
	v_readlane_b32 s7, v252, 23
	v_readlane_b32 s14, v252, 42
	v_readlane_b32 s15, v252, 43
	v_readlane_b32 s18, v252, 46
	v_readlane_b32 s19, v252, 47
	v_readlane_b32 s20, v252, 48
	v_readlane_b32 s21, v252, 49
	v_readlane_b32 s22, v252, 50
	v_readlane_b32 s23, v252, 51
	global_load_dwordx4 v[192:195], v[42:43], off
	global_load_dwordx4 v[196:199], v[42:43], off offset:1024
	global_load_dwordx4 v[200:203], v[42:43], off offset:2048
	global_load_dwordx4 v[204:207], v[42:43], off offset:3072
	s_waitcnt vmcnt(0)
	s_branch .LBB0_2154

.Lnp_bp_2154:
	ds_bpermute_b32 v44, v1, v36
	s_mov_b32 s0, 0xf800000
	v_add_u32_e32 v34, s60, v34
	v_add_u32_e32 v46, s4, v46
	v_lshl_add_u64 v[42:43], v[42:43], 0, s[10:11]
	global_load_dwordx4 v[192:195], v[42:43], off
	global_load_dwordx4 v[196:199], v[42:43], off offset:1024
	global_load_dwordx4 v[200:203], v[42:43], off offset:2048
	global_load_dwordx4 v[204:207], v[42:43], off offset:3072
	s_waitcnt lgkmcnt(0)
	v_add_f32_e32 v36, v36, v44
	ds_bpermute_b32 v44, v234, v36
	s_waitcnt lgkmcnt(0)
	v_add_f32_e32 v36, v36, v44
	ds_bpermute_b32 v44, v235, v36
	s_waitcnt lgkmcnt(0)
	v_add_f32_e32 v36, v36, v44
	ds_bpermute_b32 v44, v236, v36
	s_waitcnt lgkmcnt(0)
	v_add_f32_e32 v36, v36, v44
	ds_bpermute_b32 v44, v237, v36
	s_waitcnt lgkmcnt(0)
	v_add_f32_e32 v36, v36, v44
	ds_bpermute_b32 v44, v238, v36
	s_waitcnt lgkmcnt(0)
	v_add_f32_e32 v36, v36, v44
	v_fmamk_f32 v36, v36, 0x3a800000, v35
	v_mul_f32_e32 v44, 0x4f800000, v36
	v_cmp_gt_f32_e32 vcc, s0, v36
	s_nop 1
	v_cndmask_b32_e32 v36, v36, v44, vcc
	v_sqrt_f32_e32 v44, v36
	s_nop 0
	v_add_u32_e32 v45, -1, v44
	v_add_u32_e32 v50, 1, v44
	v_fma_f32 v51, -v45, v44, v36
	v_fma_f32 v52, -v50, v44, v36
	v_cmp_ge_f32_e64 s[0:1], 0, v51
	s_nop 1
	v_cndmask_b32_e64 v44, v44, v45, s[0:1]
	v_cmp_lt_f32_e64 s[0:1], 0, v52
	s_nop 1
	v_cndmask_b32_e64 v44, v44, v50, s[0:1]
	v_mul_f32_e32 v45, 0x37800000, v44
	v_cndmask_b32_e32 v44, v44, v45, vcc
	v_cmp_class_f32_e32 vcc, v36, v47
	s_nop 1
	v_cndmask_b32_e32 v36, v44, v36, vcc
	v_div_scale_f32 v44, s[0:1], v36, v36, 1.0
	v_rcp_f32_e32 v45, v44
	v_div_scale_f32 v50, vcc, 1.0, v36, 1.0
	s_mov_b32 s0, 0x83ff
	v_fma_f32 v51, -v44, v45, 1.0
	v_fmac_f32_e32 v45, v51, v45
	v_mul_f32_e32 v51, v50, v45
	v_fma_f32 v52, -v44, v51, v50
	v_fmac_f32_e32 v51, v52, v45
	v_fma_f32 v44, -v44, v51, v50
	v_div_fmas_f32 v44, v44, v45, v51
	v_div_fixup_f32 v36, v44, v36, 1.0
	v_mul_f32_e32 v18, v18, v36
	v_mul_f32_e32 v19, v19, v36
	v_mul_f32_e32 v20, v20, v36
	v_mul_f32_e32 v18, v10, v18
	v_mul_f32_e32 v19, v11, v19
	v_cvt_pk_bf16_f32 v18, v18, v19
	v_mul_f32_e32 v19, v12, v20
	v_mul_f32_e32 v20, v21, v36
	v_mul_f32_e32 v20, v13, v20
	v_cvt_pk_bf16_f32 v19, v19, v20
	global_store_dwordx2 v[40:41], v[18:19], off offset:-1024
	v_mul_f32_e32 v18, v22, v36
	v_mul_f32_e32 v19, v23, v36
	v_mul_f32_e32 v18, v2, v18
	v_mul_f32_e32 v19, v3, v19
	v_cvt_pk_bf16_f32 v18, v18, v19
	v_mul_f32_e32 v19, v24, v36
	v_mul_f32_e32 v19, v4, v19
	v_mul_f32_e32 v20, v25, v36
	v_mul_f32_e32 v20, v5, v20
	v_cvt_pk_bf16_f32 v19, v19, v20
	global_store_dwordx2 v[40:41], v[18:19], off offset:-512
	v_mul_f32_e32 v18, v26, v36
	v_mul_f32_e32 v19, v27, v36
	v_mul_f32_e32 v18, v6, v18
	v_mul_f32_e32 v19, v7, v19
	v_cvt_pk_bf16_f32 v18, v18, v19
	v_mul_f32_e32 v19, v28, v36
	v_mul_f32_e32 v19, v8, v19
	v_mul_f32_e32 v20, v29, v36
	v_mul_f32_e32 v20, v9, v20
	v_cvt_pk_bf16_f32 v19, v19, v20
	global_store_dwordx2 v[40:41], v[18:19], off
	v_mul_f32_e32 v18, v30, v36
	v_mul_f32_e32 v19, v31, v36
	v_mul_f32_e32 v18, v14, v18
	v_mul_f32_e32 v19, v15, v19
	v_cvt_pk_bf16_f32 v18, v18, v19
	v_mul_f32_e32 v19, v32, v36
	v_mul_f32_e32 v19, v16, v19
	v_mul_f32_e32 v20, v33, v36
	v_cmp_lt_i32_e32 vcc, s0, v34
	v_mul_f32_e32 v20, v17, v20
	v_cvt_pk_bf16_f32 v19, v19, v20
	global_store_dwordx2 v[40:41], v[18:19], off offset:512
	v_lshl_add_u64 v[40:41], v[40:41], 0, s[8:9]
	s_or_b64 s[12:13], vcc, s[12:13]
	s_andn2_b64 exec, exec, s[12:13]
	s_cbranch_execz .LBB0_2162

.LBB0_3304:
	v_mov_b32_e32 v3, v106
	s_waitcnt vmcnt(0)
	ds_write_b128 v126, v[54:57]
	ds_write_b128 v127, v[58:61]
	ds_write_b128 v128, v[62:65]
	s_waitcnt lgkmcnt(0)
	s_barrier
	s_mov_b32 s23, s51
	v_and_b32_e32 v4, 31, v3
	v_ashrrev_i32_e32 v3, 5, v3
	v_mul_u32_u24_e32 v22, 0x310, v4
	v_or_b32_e32 v5, s54, v4
	v_lshlrev_b32_e32 v23, 4, v3
	v_mul_u32_u24_e32 v5, s36, v5
	v_add3_u32 v38, v22, v23, s93
	v_mov_b32_e32 v22, 0
	v_add3_u32 v5, v5, v23, s92
	v_mov_b32_e32 v23, v22
	v_mov_b32_e32 v24, v22
	v_mov_b32_e32 v25, v22
	v_mov_b32_e32 v26, v22
	v_mov_b32_e32 v27, v22
	v_mov_b32_e32 v28, v22
	v_mov_b32_e32 v29, v22
	v_mov_b32_e32 v30, v22
	v_mov_b32_e32 v31, v22
	v_mov_b32_e32 v32, v22
	v_mov_b32_e32 v33, v22
	v_mov_b32_e32 v34, v22
	v_mov_b32_e32 v35, v22
	v_mov_b32_e32 v36, v22
	v_mov_b32_e32 v37, v22
	ds_read_b128 v[40:43], v38
	ds_read_b128 v[44:47], v5
	ds_read_b128 v[54:57], v38 offset:32
	ds_read_b128 v[58:61], v5 offset:32
	s_cmp_eq_u32 s23, 2
	s_cbranch_scc1 .Lrs0_fin2_3305
	ds_read_b128 v[176:179], v38 offset:64
	ds_read_b128 v[180:183], v5 offset:64
	ds_read_b128 v[184:187], v38 offset:96
	ds_read_b128 v[188:191], v5 offset:96
	s_waitcnt lgkmcnt(6)
	v_mfma_f32_32x32x16_bf16 v[22:37], v[40:43], v[44:47], v[22:37]
	s_waitcnt lgkmcnt(4)
	v_mfma_f32_32x32x16_bf16 v[22:37], v[54:57], v[58:61], v[22:37]
	s_cmp_eq_u32 s23, 4
	s_cbranch_scc1 .Lrs0_fin4_3305
	ds_read_b128 v[40:43], v38 offset:128
	ds_read_b128 v[44:47], v5 offset:128
	ds_read_b128 v[54:57], v38 offset:160
	ds_read_b128 v[58:61], v5 offset:160
	s_waitcnt lgkmcnt(6)
	v_mfma_f32_32x32x16_bf16 v[22:37], v[176:179], v[180:183], v[22:37]
	s_waitcnt lgkmcnt(4)
	v_mfma_f32_32x32x16_bf16 v[22:37], v[184:187], v[188:191], v[22:37]
	ds_read_b128 v[176:179], v38 offset:192
	ds_read_b128 v[180:183], v5 offset:192
	ds_read_b128 v[184:187], v38 offset:224
	ds_read_b128 v[188:191], v5 offset:224
	s_waitcnt lgkmcnt(6)
	v_mfma_f32_32x32x16_bf16 v[22:37], v[40:43], v[44:47], v[22:37]
	s_waitcnt lgkmcnt(4)
	v_mfma_f32_32x32x16_bf16 v[22:37], v[54:57], v[58:61], v[22:37]
	ds_read_b128 v[40:43], v38 offset:256
	ds_read_b128 v[44:47], v5 offset:256
	ds_read_b128 v[54:57], v38 offset:288
	ds_read_b128 v[58:61], v5 offset:288
	s_waitcnt lgkmcnt(6)
	v_mfma_f32_32x32x16_bf16 v[22:37], v[176:179], v[180:183], v[22:37]
	s_waitcnt lgkmcnt(4)
	v_mfma_f32_32x32x16_bf16 v[22:37], v[184:187], v[188:191], v[22:37]
	s_waitcnt lgkmcnt(2)
	v_mfma_f32_32x32x16_bf16 v[22:37], v[40:43], v[44:47], v[22:37]
	s_waitcnt lgkmcnt(0)
	v_mfma_f32_32x32x16_bf16 v[22:37], v[54:57], v[58:61], v[22:37]
	s_branch .Lrs0_done_3305

.Lrs0_done_3305:
	s_nop 3
	s_movk_i32 s24, 0x240
	v_lshlrev_b32_e32 v4, 1, v4
	v_mul_lo_u32 v3, v3, s24
	v_add3_u32 v3, s88, v4, v3
	v_cvt_pk_bf16_f32 v4, v22, v2
	ds_write_b16 v3, v4
	v_cvt_pk_bf16_f32 v4, v23, v2
	ds_write_b16 v3, v4 offset:144
	v_cvt_pk_bf16_f32 v4, v24, v2
	ds_write_b16 v3, v4 offset:288
	v_cvt_pk_bf16_f32 v4, v25, v2
	ds_write_b16 v3, v4 offset:432
	v_cvt_pk_bf16_f32 v4, v26, v2
	ds_write_b16 v3, v4 offset:1152
	v_cvt_pk_bf16_f32 v4, v27, v2
	ds_write_b16 v3, v4 offset:1296
	v_cvt_pk_bf16_f32 v4, v28, v2
	ds_write_b16 v3, v4 offset:1440
	v_cvt_pk_bf16_f32 v4, v29, v2
	ds_write_b16 v3, v4 offset:1584
	v_cvt_pk_bf16_f32 v4, v30, v2
	ds_write_b16 v3, v4 offset:2304
	v_cvt_pk_bf16_f32 v4, v31, v2
	ds_write_b16 v3, v4 offset:2448
	v_cvt_pk_bf16_f32 v4, v32, v2
	ds_write_b16 v3, v4 offset:2592
	v_cvt_pk_bf16_f32 v4, v33, v2
	ds_write_b16 v3, v4 offset:2736
	v_cvt_pk_bf16_f32 v4, v34, v2
	ds_write_b16 v3, v4 offset:3456
	v_cvt_pk_bf16_f32 v4, v35, v2
	s_lshl_b32 s23, s25, 5
	ds_write_b16 v3, v4 offset:3600
	v_cvt_pk_bf16_f32 v4, v36, v2
	ds_write_b16 v3, v4 offset:3744
	v_cvt_pk_bf16_f32 v4, v37, v2
	s_sub_i32 s24, s57, s23
	ds_write_b16 v3, v4 offset:3888
	v_mov_b32_e32 v31, 0
	s_cmp_lt_i32 s55, s24
	v_mov_b32_e32 v30, 0
	v_mov_b32_e32 v4, 0
	v_mov_b32_e32 v5, 0
	v_mov_b32_e32 v22, 0
	v_mov_b32_e32 v23, 0
	v_mov_b32_e32 v3, 0
	v_mov_b32_e32 v32, 0
	s_waitcnt lgkmcnt(0)
	s_barrier
	s_cbranch_scc0 .LBB0_3308
	v_add_u32_e32 v5, s90, v107
	v_add_u32_e32 v22, s90, v108
	v_add_u32_e32 v23, s90, v109
	ds_read_u16 v5, v5
	v_add_u32_e32 v24, s90, v110
	ds_read_u16 v22, v22
	ds_read_u16 v23, v23
	ds_read_u16 v26, v24
	v_lshlrev_b32_e32 v3, 16, v133
	v_mul_f32_e32 v28, v150, v3
	s_waitcnt lgkmcnt(2)
	v_lshlrev_b32_e32 v22, 16, v22
	v_add_f32_e32 v22, v153, v22
	v_mul_f32_e32 v22, 0xbfb8aa3b, v22
	v_exp_f32_e32 v24, v22
	v_lshlrev_b32_e32 v5, 16, v5
	v_add_f32_e32 v5, v148, v5
	v_mul_f32_e32 v5, 0xbfb8aa3b, v5
	v_add_f32_e32 v24, 1.0, v24
	v_rcp_f32_e32 v27, v24
	v_mul_f32_e32 v24, v28, v28
	s_waitcnt lgkmcnt(1)
	v_lshlrev_b32_e32 v23, 16, v23
	v_exp_f32_e32 v5, v5
	v_mov_b32_dpp v24, v24 quad_perm:[1,0,3,2] row_mask:0xf bank_mask:0xf bound_ctrl:1
	v_fmac_f32_e32 v24, v28, v28
	v_add_f32_e32 v23, v149, v23
	v_mul_f32_e32 v23, 0xbfb8aa3b, v23
	v_add_f32_dpp v24, v24, v24 quad_perm:[2,3,0,1] row_mask:0xf bank_mask:0xf bound_ctrl:1
	v_exp_f32_e32 v23, v23
	v_lshlrev_b32_e32 v4, 16, v137
	v_add_f32_dpp v24, v24, v24 row_ror:4 row_mask:0xf bank_mask:0xf bound_ctrl:1
	v_add_f32_e32 v5, 1.0, v5
	v_rcp_f32_e32 v22, v5
	v_add_f32_dpp v24, v24, v24 row_ror:8 row_mask:0xf bank_mask:0xf bound_ctrl:1
	v_sub_f32_e32 v5, v142, v4
	v_readlane_b32 s23, v24, 16
	v_readlane_b32 s30, v24, 48
	v_readlane_b32 s28, v24, 0
	v_readlane_b32 s29, v24, 32
	v_mov_b32_e32 v24, s23
	v_mov_b32_e32 v25, s30
	v_pk_add_f32 v[24:25], s[28:29], v[24:25]
	v_lshlrev_b32_e32 v32, 16, v132
	v_add_f32_e32 v24, v24, v25
	v_sqrt_f32_e32 v25, v24
	v_mul_f32_e32 v24, v5, v27
	v_add_f32_e32 v5, 1.0, v23
	v_rcp_f32_e32 v23, v5
	v_xor_b32_e32 v5, 0x80000000, v25
	v_min_f32_e32 v5, 0xab8cbccc, v5
	v_rcp_f32_e32 v5, v5
	v_add_f32_e32 v25, -1.0, v23
	v_fma_f32 v25, v151, v25, 1.0
	v_mul_f32_e32 v30, v25, v3
	v_mul_f32_e32 v31, v28, v5
	v_mul_f32_e32 v5, v30, v32
	v_mul_f32_e32 v25, v152, v5
	v_xor_b32_e32 v83, 0x80000000, v31
	v_pk_mul_f32 v[22:23], v[22:23], v[82:83]
	v_mov_b32_dpp v25, v25 quad_perm:[1,0,3,2] row_mask:0xf bank_mask:0xf bound_ctrl:1
	v_fmac_f32_e32 v25, v152, v5
	s_waitcnt lgkmcnt(0)
	v_lshlrev_b32_e32 v3, 16, v26
	v_add_f32_dpp v5, v25, v25 quad_perm:[2,3,0,1] row_mask:0xf bank_mask:0xf bound_ctrl:1
	s_nop 1
	v_add_f32_dpp v5, v5, v5 row_ror:4 row_mask:0xf bank_mask:0xf bound_ctrl:1
	s_nop 1
	v_add_f32_dpp v5, v5, v5 row_ror:8 row_mask:0xf bank_mask:0xf bound_ctrl:1
	s_nop 0
	v_readlane_b32 s28, v5, 16
	v_readlane_b32 s23, v5, 0
	s_nop 0
	v_mov_b32_e32 v25, s28
	v_readlane_b32 s28, v5, 48
	v_add_f32_e32 v25, s23, v25
	v_readlane_b32 s23, v5, 32
	v_mov_b32_e32 v5, s28
	s_nop 0
	v_add_f32_e32 v5, s23, v5
	v_pk_add_f32 v[4:5], v[24:25], v[4:5]

.LBB0_3326:
	v_mov_b32_e32 v4, v106
	s_waitcnt lgkmcnt(0)
	s_barrier
	s_mov_b64 s[34:35], -1
	v_and_b32_e32 v3, 31, v4
	v_ashrrev_i32_e32 v39, 5, v4
	v_lshlrev_b32_e32 v4, 4, v39
	v_mul_u32_u24_e32 v5, 0x90, v3
	s_and_b64 vcc, exec, s[48:49]
	s_cbranch_vccz .LBB0_3328
	v_add3_u32 v38, s38, v5, v4
	ds_read_b128 v[22:25], v38
	v_or_b32_e32 v26, s54, v3
	v_mul_u32_u24_e32 v26, 0x90, v26
	v_add3_u32 v48, 0, v26, v4
	ds_read_b128 v[26:29], v48 offset:41472
	ds_read_b128 v[40:43], v38 offset:32
	ds_read_b128 v[44:47], v48 offset:41504
	s_mov_b64 s[34:35], 0
	ds_read_b128 v[176:179], v38 offset:64
	ds_read_b128 v[180:183], v48 offset:41536
	ds_read_b128 v[184:187], v38 offset:96
	ds_read_b128 v[188:191], v48 offset:41568
	s_waitcnt lgkmcnt(6)
	v_mfma_f32_32x32x16_bf16 v[22:37], v[22:25], v[26:29], 0
	s_waitcnt lgkmcnt(4)
	v_mfma_f32_32x32x16_bf16 v[22:37], v[40:43], v[44:47], v[22:37]
	s_waitcnt lgkmcnt(2)
	v_mfma_f32_32x32x16_bf16 v[22:37], v[176:179], v[180:183], v[22:37]
	s_waitcnt lgkmcnt(0)
	v_mfma_f32_32x32x16_bf16 v[22:37], v[184:187], v[188:191], v[22:37]
.LBB0_3328:
	s_andn2_b64 vcc, exec, s[34:35]
	s_cbranch_vccnz .LBB0_3364
	v_add3_u32 v38, s40, v5, v4
	s_nop 8
	ds_read_b128 v[22:25], v38
	v_add3_u32 v4, s41, v5, v4
	ds_read_b128 v[26:29], v4
	ds_read_b128 v[40:43], v38 offset:32
	ds_read_b128 v[44:47], v4 offset:32
	v_lshlrev_b32_e32 v5, 2, v39
	s_mov_b64 s[34:35], -1
	s_and_b64 vcc, exec, s[60:61]
	ds_read_b128 v[176:179], v38 offset:64
	ds_read_b128 v[180:183], v4 offset:64
	ds_read_b128 v[184:187], v38 offset:96
	ds_read_b128 v[188:191], v4 offset:96
	s_waitcnt lgkmcnt(6)
	v_mfma_f32_32x32x16_bf16 v[22:37], v[22:25], v[26:29], 0
	s_waitcnt lgkmcnt(4)
	v_mfma_f32_32x32x16_bf16 v[22:37], v[40:43], v[44:47], v[22:37]
	s_waitcnt lgkmcnt(2)
	v_mfma_f32_32x32x16_bf16 v[22:37], v[176:179], v[180:183], v[22:37]
	v_lshl_add_u32 v4, v3, 1, s44
	s_waitcnt lgkmcnt(0)
	v_mfma_f32_32x32x16_bf16 v[22:37], v[184:187], v[188:191], v[22:37]
	s_cbranch_vccz .LBB0_3331
	v_cmp_lt_i32_e32 vcc, v3, v5
	s_movk_i32 s34, 0x140
	s_nop 0
	v_cndmask_b32_e64 v38, 0, 1, vcc
	v_cmp_le_i32_e32 vcc, v3, v5
	s_nop 1
	v_cndmask_b32_e64 v40, 0, 1, vcc
	v_cndmask_b32_e64 v38, v40, v38, s[4:5]
	v_and_b32_e32 v38, 1, v38
	v_cmp_eq_u32_e32 vcc, 1, v38
	v_mad_u64_u32 v[40:41], s[34:35], v39, s34, v[4:5]
	s_nop 0
	v_cndmask_b32_e32 v38, 0, v22, vcc
	v_cvt_pk_bf16_f32 v38, v38, v2
	ds_write_b16 v40, v38
	s_mov_b64 s[34:35], 0
